# m3 + accumulator zeroing in four GEMM unit prologues as 64-bit moves (64 v_mov_b64 instead of 127 v_mov_b32): strategy 7 instruction selection
# speedup vs baseline: 1.0030x; 1.0023x over previous
.LBB0_418:
	s_ashr_i32 s51, s50, 31
	s_lshl_b64 s[10:11], s[50:51], 19
	s_add_u32 s52, s12, s10
	s_addc_u32 s53, s13, s11
	s_and_b64 s[10:11], s[38:39], exec
	s_cselect_b32 s34, s53, s9
	s_cselect_b32 s35, s52, s8
	s_ashr_i32 s49, s48, 31
	s_lshl_b64 s[10:11], s[48:49], 19
	s_add_u32 s56, s14, s10
	s_addc_u32 s57, s15, s11
	s_and_b64 s[10:11], s[38:39], exec
	s_cselect_b32 s36, s57, s1
	s_cselect_b32 s37, s56, s0
	s_add_u32 s49, s0, 0x100
	s_addc_u32 s51, s1, 0
	s_add_u32 s0, s8, 0x40080
	v_mov_b32_e32 v2, 0
	s_addc_u32 s1, s9, 0
	s_mov_b32 s55, -2
	v_mov_b32_e32 v3, 0
	v_mov_b64_e32 v[4:5], 0
	v_mov_b64_e32 v[6:7], 0
	v_mov_b64_e32 v[8:9], 0
	v_mov_b64_e32 v[10:11], 0
	v_mov_b64_e32 v[12:13], 0
	v_mov_b64_e32 v[14:15], 0
	v_mov_b64_e32 v[16:17], 0
	v_mov_b64_e32 v[18:19], 0
	v_mov_b64_e32 v[20:21], 0
	v_mov_b64_e32 v[22:23], 0
	v_mov_b64_e32 v[24:25], 0
	v_mov_b64_e32 v[26:27], 0
	v_mov_b64_e32 v[28:29], 0
	v_mov_b64_e32 v[30:31], 0
	v_mov_b64_e32 v[32:33], 0
	v_mov_b64_e32 v[34:35], 0
	v_mov_b64_e32 v[36:37], 0
	v_mov_b64_e32 v[38:39], 0
	v_mov_b64_e32 v[40:41], 0
	v_mov_b64_e32 v[42:43], 0
	v_mov_b64_e32 v[44:45], 0
	v_mov_b64_e32 v[46:47], 0
	v_mov_b64_e32 v[48:49], 0
	v_mov_b64_e32 v[50:51], 0
	v_mov_b64_e32 v[52:53], 0
	v_mov_b64_e32 v[54:55], 0
	v_mov_b64_e32 v[56:57], 0
	v_mov_b64_e32 v[58:59], 0
	v_mov_b64_e32 v[60:61], 0
	v_mov_b64_e32 v[62:63], 0
	v_mov_b64_e32 v[64:65], 0
	v_mov_b64_e32 v[66:67], 0
	v_mov_b64_e32 v[68:69], 0
	v_mov_b64_e32 v[70:71], 0
	v_mov_b64_e32 v[72:73], 0
	v_mov_b64_e32 v[74:75], 0
	v_mov_b64_e32 v[76:77], 0
	v_mov_b64_e32 v[78:79], 0
	v_mov_b64_e32 v[80:81], 0
	v_mov_b64_e32 v[82:83], 0
	v_mov_b64_e32 v[84:85], 0
	v_mov_b64_e32 v[86:87], 0
	v_mov_b64_e32 v[88:89], 0
	v_mov_b64_e32 v[90:91], 0
	v_mov_b64_e32 v[92:93], 0
	v_mov_b64_e32 v[94:95], 0
	v_mov_b64_e32 v[96:97], 0
	v_mov_b64_e32 v[98:99], 0
	v_mov_b64_e32 v[100:101], 0
	v_mov_b64_e32 v[102:103], 0
	v_mov_b64_e32 v[104:105], 0
	v_mov_b64_e32 v[106:107], 0
	v_mov_b64_e32 v[108:109], 0
	v_mov_b64_e32 v[110:111], 0
	v_mov_b64_e32 v[112:113], 0
	v_mov_b64_e32 v[114:115], 0
	v_mov_b64_e32 v[116:117], 0
	v_mov_b64_e32 v[118:119], 0
	v_mov_b64_e32 v[120:121], 0
	v_mov_b64_e32 v[122:123], 0
	v_mov_b64_e32 v[124:125], 0
	v_mov_b64_e32 v[126:127], 0
	v_mov_b64_e32 v[128:129], 0

.LBB0_795:
	s_ashr_i32 s57, s56, 31
	s_lshl_b64 s[10:11], s[56:57], 19
	s_add_u32 s58, s12, s10
	s_addc_u32 s59, s13, s11
	s_and_b64 s[10:11], s[40:41], exec
	s_cselect_b32 s36, s59, s9
	s_cselect_b32 s37, s58, s8
	s_ashr_i32 s53, s52, 31
	s_lshl_b64 s[10:11], s[52:53], 19
	s_add_u32 s60, s14, s10
	s_addc_u32 s61, s15, s11
	s_and_b64 s[10:11], s[40:41], exec
	s_cselect_b32 s42, s61, s1
	s_cselect_b32 s43, s60, s0
	s_add_u32 s53, s0, 0x100
	s_addc_u32 s54, s1, 0
	s_add_u32 s0, s8, 0x40080
	v_mov_b32_e32 v2, 0
	s_addc_u32 s1, s9, 0
	s_mov_b32 s55, -2
	v_mov_b32_e32 v3, 0
	v_mov_b64_e32 v[4:5], 0
	v_mov_b64_e32 v[6:7], 0
	v_mov_b64_e32 v[8:9], 0
	v_mov_b64_e32 v[10:11], 0
	v_mov_b64_e32 v[12:13], 0
	v_mov_b64_e32 v[14:15], 0
	v_mov_b64_e32 v[16:17], 0
	v_mov_b64_e32 v[18:19], 0
	v_mov_b64_e32 v[20:21], 0
	v_mov_b64_e32 v[22:23], 0
	v_mov_b64_e32 v[24:25], 0
	v_mov_b64_e32 v[26:27], 0
	v_mov_b64_e32 v[28:29], 0
	v_mov_b64_e32 v[30:31], 0
	v_mov_b64_e32 v[32:33], 0
	v_mov_b64_e32 v[34:35], 0
	v_mov_b64_e32 v[36:37], 0
	v_mov_b64_e32 v[38:39], 0
	v_mov_b64_e32 v[40:41], 0
	v_mov_b64_e32 v[42:43], 0
	v_mov_b64_e32 v[44:45], 0
	v_mov_b64_e32 v[46:47], 0
	v_mov_b64_e32 v[48:49], 0
	v_mov_b64_e32 v[50:51], 0
	v_mov_b64_e32 v[52:53], 0
	v_mov_b64_e32 v[54:55], 0
	v_mov_b64_e32 v[56:57], 0
	v_mov_b64_e32 v[58:59], 0
	v_mov_b64_e32 v[60:61], 0
	v_mov_b64_e32 v[62:63], 0
	v_mov_b64_e32 v[64:65], 0
	v_mov_b64_e32 v[66:67], 0
	v_mov_b64_e32 v[68:69], 0
	v_mov_b64_e32 v[70:71], 0
	v_mov_b64_e32 v[72:73], 0
	v_mov_b64_e32 v[74:75], 0
	v_mov_b64_e32 v[76:77], 0
	v_mov_b64_e32 v[78:79], 0
	v_mov_b64_e32 v[80:81], 0
	v_mov_b64_e32 v[82:83], 0
	v_mov_b64_e32 v[84:85], 0
	v_mov_b64_e32 v[86:87], 0
	v_mov_b64_e32 v[88:89], 0
	v_mov_b64_e32 v[90:91], 0
	v_mov_b64_e32 v[92:93], 0
	v_mov_b64_e32 v[94:95], 0
	v_mov_b64_e32 v[96:97], 0
	v_mov_b64_e32 v[98:99], 0
	v_mov_b64_e32 v[100:101], 0
	v_mov_b64_e32 v[102:103], 0
	v_mov_b64_e32 v[104:105], 0
	v_mov_b64_e32 v[106:107], 0
	v_mov_b64_e32 v[108:109], 0
	v_mov_b64_e32 v[110:111], 0
	v_mov_b64_e32 v[112:113], 0
	v_mov_b64_e32 v[114:115], 0
	v_mov_b64_e32 v[116:117], 0
	v_mov_b64_e32 v[118:119], 0
	v_mov_b64_e32 v[120:121], 0
	v_mov_b64_e32 v[122:123], 0
	v_mov_b64_e32 v[124:125], 0
	v_mov_b64_e32 v[126:127], 0
	v_mov_b64_e32 v[128:129], 0

.LBB0_2961:
	s_ashr_i32 s43, s42, 31
	v_cmp_lt_i64_e32 vcc, s[10:11], v[190:191]
	s_lshl_b64 s[10:11], s[42:43], 18
	s_add_u32 s44, s15, s10
	s_addc_u32 s45, s16, s11
	s_and_b64 s[10:11], vcc, exec
	s_cselect_b32 s12, s45, s9
	s_cselect_b32 s13, s44, s8
	s_ashr_i32 s41, s40, 31
	s_lshl_b64 s[10:11], s[40:41], 18
	s_add_u32 s48, s17, s10
	s_addc_u32 s49, s18, s11
	s_and_b64 s[10:11], vcc, exec
	s_cselect_b32 s37, s49, s1
	s_cselect_b32 s41, s48, s0
	s_add_u32 s43, s0, 0x100
	s_addc_u32 s50, s1, 0
	s_add_u32 s0, s8, 0x20080
	v_mov_b32_e32 v2, 0
	s_addc_u32 s1, s9, 0
	s_mov_b32 s51, -2
	v_mov_b32_e32 v3, 0
	v_mov_b64_e32 v[4:5], 0
	v_mov_b64_e32 v[6:7], 0
	v_mov_b64_e32 v[8:9], 0
	v_mov_b64_e32 v[10:11], 0
	v_mov_b64_e32 v[12:13], 0
	v_mov_b64_e32 v[14:15], 0
	v_mov_b64_e32 v[16:17], 0
	v_mov_b64_e32 v[18:19], 0
	v_mov_b64_e32 v[20:21], 0
	v_mov_b64_e32 v[22:23], 0
	v_mov_b64_e32 v[24:25], 0
	v_mov_b64_e32 v[26:27], 0
	v_mov_b64_e32 v[28:29], 0
	v_mov_b64_e32 v[30:31], 0
	v_mov_b64_e32 v[32:33], 0
	v_mov_b64_e32 v[34:35], 0
	v_mov_b64_e32 v[36:37], 0
	v_mov_b64_e32 v[38:39], 0
	v_mov_b64_e32 v[40:41], 0
	v_mov_b64_e32 v[42:43], 0
	v_mov_b64_e32 v[44:45], 0
	v_mov_b64_e32 v[46:47], 0
	v_mov_b64_e32 v[48:49], 0
	v_mov_b64_e32 v[50:51], 0
	v_mov_b64_e32 v[52:53], 0
	v_mov_b64_e32 v[54:55], 0
	v_mov_b64_e32 v[56:57], 0
	v_mov_b64_e32 v[58:59], 0
	v_mov_b64_e32 v[60:61], 0
	v_mov_b64_e32 v[62:63], 0
	v_mov_b64_e32 v[64:65], 0
	v_mov_b64_e32 v[66:67], 0
	v_mov_b64_e32 v[68:69], 0
	v_mov_b64_e32 v[70:71], 0
	v_mov_b64_e32 v[72:73], 0
	v_mov_b64_e32 v[74:75], 0
	v_mov_b64_e32 v[76:77], 0
	v_mov_b64_e32 v[78:79], 0
	v_mov_b64_e32 v[80:81], 0
	v_mov_b64_e32 v[82:83], 0
	v_mov_b64_e32 v[84:85], 0
	v_mov_b64_e32 v[86:87], 0
	v_mov_b64_e32 v[88:89], 0
	v_mov_b64_e32 v[90:91], 0
	v_mov_b64_e32 v[92:93], 0
	v_mov_b64_e32 v[94:95], 0
	v_mov_b64_e32 v[96:97], 0
	v_mov_b64_e32 v[98:99], 0
	v_mov_b64_e32 v[100:101], 0
	v_mov_b64_e32 v[102:103], 0
	v_mov_b64_e32 v[104:105], 0
	v_mov_b64_e32 v[106:107], 0
	v_mov_b64_e32 v[108:109], 0
	v_mov_b64_e32 v[110:111], 0
	v_mov_b64_e32 v[112:113], 0
	v_mov_b64_e32 v[114:115], 0
	v_mov_b64_e32 v[116:117], 0
	v_mov_b64_e32 v[118:119], 0
	v_mov_b64_e32 v[120:121], 0
	v_mov_b64_e32 v[122:123], 0
	v_mov_b64_e32 v[124:125], 0
	v_mov_b64_e32 v[126:127], 0
	v_mov_b64_e32 v[128:129], 0

.LBB0_3095:
	s_ashr_i32 s45, s44, 31
	v_cmp_lt_i64_e32 vcc, s[10:11], v[190:191]
	s_lshl_b64 s[10:11], s[44:45], 18
	s_add_u32 s46, s15, s10
	s_addc_u32 s47, s16, s11
	s_and_b64 s[10:11], vcc, exec
	s_cselect_b32 s12, s47, s9
	s_cselect_b32 s13, s46, s8
	s_ashr_i32 s43, s42, 31
	s_lshl_b64 s[10:11], s[42:43], 18
	s_add_u32 s48, s17, s10
	s_addc_u32 s49, s18, s11
	s_and_b64 s[10:11], vcc, exec
	s_cselect_b32 s37, s49, s1
	s_cselect_b32 s43, s48, s0
	s_add_u32 s45, s0, 0x100
	s_addc_u32 s50, s1, 0
	s_add_u32 s0, s8, 0x20080
	v_mov_b32_e32 v2, 0
	s_addc_u32 s1, s9, 0
	s_mov_b32 s51, -2
	v_mov_b32_e32 v3, 0
	v_mov_b64_e32 v[4:5], 0
	v_mov_b64_e32 v[6:7], 0
	v_mov_b64_e32 v[8:9], 0
	v_mov_b64_e32 v[10:11], 0
	v_mov_b64_e32 v[12:13], 0
	v_mov_b64_e32 v[14:15], 0
	v_mov_b64_e32 v[16:17], 0
	v_mov_b64_e32 v[18:19], 0
	v_mov_b64_e32 v[20:21], 0
	v_mov_b64_e32 v[22:23], 0
	v_mov_b64_e32 v[24:25], 0
	v_mov_b64_e32 v[26:27], 0
	v_mov_b64_e32 v[28:29], 0
	v_mov_b64_e32 v[30:31], 0
	v_mov_b64_e32 v[32:33], 0
	v_mov_b64_e32 v[34:35], 0
	v_mov_b64_e32 v[36:37], 0
	v_mov_b64_e32 v[38:39], 0
	v_mov_b64_e32 v[40:41], 0
	v_mov_b64_e32 v[42:43], 0
	v_mov_b64_e32 v[44:45], 0
	v_mov_b64_e32 v[46:47], 0
	v_mov_b64_e32 v[48:49], 0
	v_mov_b64_e32 v[50:51], 0
	v_mov_b64_e32 v[52:53], 0
	v_mov_b64_e32 v[54:55], 0
	v_mov_b64_e32 v[56:57], 0
	v_mov_b64_e32 v[58:59], 0
	v_mov_b64_e32 v[60:61], 0
	v_mov_b64_e32 v[62:63], 0
	v_mov_b64_e32 v[64:65], 0
	v_mov_b64_e32 v[66:67], 0
	v_mov_b64_e32 v[68:69], 0
	v_mov_b64_e32 v[70:71], 0
	v_mov_b64_e32 v[72:73], 0
	v_mov_b64_e32 v[74:75], 0
	v_mov_b64_e32 v[76:77], 0
	v_mov_b64_e32 v[78:79], 0
	v_mov_b64_e32 v[80:81], 0
	v_mov_b64_e32 v[82:83], 0
	v_mov_b64_e32 v[84:85], 0
	v_mov_b64_e32 v[86:87], 0
	v_mov_b64_e32 v[88:89], 0
	v_mov_b64_e32 v[90:91], 0
	v_mov_b64_e32 v[92:93], 0
	v_mov_b64_e32 v[94:95], 0
	v_mov_b64_e32 v[96:97], 0
	v_mov_b64_e32 v[98:99], 0
	v_mov_b64_e32 v[100:101], 0
	v_mov_b64_e32 v[102:103], 0
	v_mov_b64_e32 v[104:105], 0
	v_mov_b64_e32 v[106:107], 0
	v_mov_b64_e32 v[108:109], 0
	v_mov_b64_e32 v[110:111], 0
	v_mov_b64_e32 v[112:113], 0
	v_mov_b64_e32 v[114:115], 0
	v_mov_b64_e32 v[116:117], 0
	v_mov_b64_e32 v[118:119], 0
	v_mov_b64_e32 v[120:121], 0
	v_mov_b64_e32 v[122:123], 0
	v_mov_b64_e32 v[124:125], 0
	v_mov_b64_e32 v[126:127], 0
	v_mov_b64_e32 v[128:129], 0
